# transpose counted vmcnt + rms gamma hoist + DIFF far/near operands computed before the tile barrier
# speedup vs baseline: 1.0160x; 1.0003x over previous
; __device__ __forceinline__ unsigned cvt_pk_bf16(float lo, float hi) { f32x2_t f = {lo, hi}; bf16x2_t r = __builtin_convertvector(f, bf16x2_t); return __builtin_bit_cast(unsigned, r); }
; #define LAS __attribute__((address_space(3)))
; #define MFMA32(a, b, c) __builtin_amdgcn_mfma_f32_32x32x16_bf16((a), (b), (c), 0, 0, 0)
; template <bool DIFF> ...
;     ...
;             const int tmn = ((const LAS int*)(lds + TMM_OFF))[2 * kt], tmx = ((const LAS int*)(lds + TMM_OFF))[2 * kt + 1];
;             const bool far_hi = __builtin_amdgcn_readfirstlane(tmn - qmax4) >= 512, far_lo = __builtin_amdgcn_readfirstlane(tmx - qmin4) <= -512;
;     ...
; #pragma unroll
;             for (int kb = 0; kb < 2; ++kb)
; #pragma unroll
;                 for (int i = 0; i < 16; ++i) { const float p = __builtin_amdgcn_exp2f(s[kb][i] - m_used); s[kb][i] = p; lsum += p; }
;         }
; #pragma unroll
;         for (int kb = 0; kb < 2; ++kb)
; #pragma unroll
;             for (int st = 0; st < 2; ++st) {
;                 u32x4 pw;
; #pragma unroll
;                 for (int q = 0; q < 4; ++q) pw[q] = cvt_pk_bf16(s[kb][8 * st + 2 * q], s[kb][8 * st + 2 * q + 1]);
;                 const bf16x8 pf = __builtin_bit_cast(bf16x8, pw);
;                 const LAS unsigned char* vp = vbuf + (r * VSTR + (2 * kb + st) * 16 + 8 * hh) * 2;
; #pragma unroll
;                 for (int d = 0; d < 4; ++d) { const bf16x8 vf = *(const LAS bf16x8*)(vp + d * 32 * VSTR * 2); O[d] = MFMA32(vf, pf, O[d]); }
;             }
;         if (more) store_tile((kt + 1) & 1);
;         __syncthreads();
.LBB0_614:
	v_mul_u32_u24_e32 v0, 0x48, v4
	v_add_lshl_u32 v175, v134, v0, 1
	v_add_u32_e32 v163, 0, v175
	s_waitcnt lgkmcnt(0)
	ds_read_b128 v[0:3], v163 offset:17408
	v_exp_f32_e32 v173, v80
	v_exp_f32_e32 v179, v81
	v_exp_f32_e32 v184, v82
	v_exp_f32_e32 v185, v83
	v_exp_f32_e32 v186, v84
	v_exp_f32_e32 v187, v85
	v_exp_f32_e32 v188, v86
	v_exp_f32_e32 v189, v87
	v_cvt_pk_bf16_f32 v4, v173, v179
	v_cvt_pk_bf16_f32 v5, v184, v185
	v_cvt_pk_bf16_f32 v6, v186, v187
	v_cvt_pk_bf16_f32 v7, v188, v189
	ds_read_b128 v[80:83], v163 offset:17440
	v_exp_f32_e32 v190, v88
	s_waitcnt lgkmcnt(1)
	v_mfma_f32_32x32x16_bf16 v[48:63], v[0:3], v[4:7], 0
	ds_read_b128 v[0:3], v163 offset:22016
	ds_read_b128 v[84:87], v163 offset:22048
	v_exp_f32_e32 v191, v89
	v_exp_f32_e32 v192, v90
	v_exp_f32_e32 v193, v91
	v_exp_f32_e32 v194, v92
	v_exp_f32_e32 v195, v93
	v_exp_f32_e32 v196, v94
	s_waitcnt lgkmcnt(1)
	v_mfma_f32_32x32x16_bf16 v[32:47], v[0:3], v[4:7], 0
	ds_read_b128 v[0:3], v163 offset:26624
	ds_read_b128 v[180:183], v163 offset:26656
	v_exp_f32_e32 v197, v95
	v_cvt_pk_bf16_f32 v92, v190, v191
	v_cvt_pk_bf16_f32 v93, v192, v193
	v_cvt_pk_bf16_f32 v94, v194, v195
	v_cvt_pk_bf16_f32 v95, v196, v197
	ds_read_b128 v[88:91], v163 offset:31264
	s_waitcnt lgkmcnt(2)
	v_mfma_f32_32x32x16_bf16 v[16:31], v[0:3], v[4:7], 0
	ds_read_b128 v[0:3], v163 offset:31232
	s_add_i32 s8, s50, s54
	s_ashr_i32 s9, s8, 31
	s_lshl_b64 s[8:9], s[8:9], 19
	s_add_u32 s8, s8, 0x15800100
	s_addc_u32 s9, s9, 0
	v_and_b32_e32 v161, 63, v138
	v_mfma_f32_32x32x16_bf16 v[48:63], v[80:83], v[92:95], v[48:63]
	v_add_f32_e32 v80, 0, v173
	v_add_f32_e32 v80, v179, v80
	v_exp_f32_e32 v179, v64
	v_add_f32_e32 v80, v184, v80
	v_add_f32_e32 v80, v185, v80
	v_add_f32_e32 v80, v186, v80
	v_add_f32_e32 v80, v187, v80
	s_waitcnt lgkmcnt(2)
	v_mfma_f32_32x32x16_bf16 v[16:31], v[180:183], v[92:95], v[16:31]
	v_exp_f32_e32 v180, v65
	v_exp_f32_e32 v181, v66
	v_exp_f32_e32 v182, v67
	ds_read_b128 v[64:67], v163 offset:17472
	v_add_f32_e32 v80, v188, v80
	v_exp_f32_e32 v183, v68
	v_exp_f32_e32 v184, v69
	s_waitcnt lgkmcnt(1)
	v_mfma_f32_32x32x16_bf16 v[0:15], v[0:3], v[4:7], 0
	v_exp_f32_e32 v185, v70
	v_add_f32_e32 v80, v189, v80
	v_add_f32_e32 v80, v190, v80
	v_add_f32_e32 v80, v191, v80
	v_add_f32_e32 v173, v192, v80
	v_cvt_pk_bf16_f32 v68, v179, v180
	v_cvt_pk_bf16_f32 v69, v181, v182
	v_mfma_f32_32x32x16_bf16 v[32:47], v[84:87], v[92:95], v[32:47]
	v_cvt_pk_bf16_f32 v70, v183, v184
	ds_read_b128 v[80:83], v163 offset:22080
	ds_read_b128 v[84:87], v163 offset:17504
	v_exp_f32_e32 v186, v75
	v_exp_f32_e32 v187, v76
	v_exp_f32_e32 v188, v77
	v_exp_f32_e32 v189, v78
	v_exp_f32_e32 v190, v79
	v_mfma_f32_32x32x16_bf16 v[0:15], v[88:91], v[92:95], v[0:15]
	v_exp_f32_e32 v92, v71
	v_exp_f32_e32 v94, v72
	v_exp_f32_e32 v95, v73
	s_mov_b32 s42, 0
	v_cvt_pk_bf16_f32 v71, v185, v92
	s_mov_b32 s43, 2
	s_waitcnt lgkmcnt(2)
	v_mfma_f32_32x32x16_bf16 v[48:63], v[64:67], v[68:71], v[48:63]
	v_add_f32_e32 v64, v193, v173
	v_add_f32_e32 v64, v194, v64
	v_add_f32_e32 v64, v195, v64
	v_add_f32_e32 v64, v196, v64
	v_add_f32_e32 v93, v197, v64
	ds_read_b128 v[64:67], v163 offset:26688
	ds_read_b128 v[88:91], v163 offset:22112
	v_exp_f32_e32 v173, v74
	s_waitcnt lgkmcnt(3)
	v_mfma_f32_32x32x16_bf16 v[32:47], v[80:83], v[68:71], v[32:47]
	ds_read_b128 v[72:75], v163 offset:31296
	ds_read_b128 v[80:83], v163 offset:26720
	ds_read_b128 v[76:79], v163 offset:31328
	s_waitcnt vmcnt(3)
	ds_write_b128 v177, v[112:115] offset:35840
	s_waitcnt vmcnt(2)
	ds_write_b128 v178, v[116:119] offset:35840
	s_waitcnt vmcnt(1)
	ds_write_b128 v139, v[120:123] offset:53248
	s_waitcnt vmcnt(0)
	ds_write_b128 v176, v[124:127] offset:53248
	s_waitcnt lgkmcnt(0)
	s_barrier
	v_mfma_f32_32x32x16_bf16 v[16:31], v[64:67], v[68:71], v[16:31]
	v_cvt_pk_bf16_f32 v64, v94, v95
	v_cvt_pk_bf16_f32 v65, v173, v186
	v_cvt_pk_bf16_f32 v66, v187, v188
	v_cvt_pk_bf16_f32 v67, v189, v190
	v_mfma_f32_32x32x16_bf16 v[0:15], v[72:75], v[68:71], v[0:15]
	v_add_f32_e32 v68, v179, v93
	v_add_f32_e32 v68, v180, v68
	v_add_f32_e32 v68, v181, v68
	v_add_f32_e32 v68, v182, v68
	v_add_f32_e32 v68, v183, v68
	v_add_f32_e32 v68, v184, v68
	v_add_f32_e32 v68, v185, v68
	v_mfma_f32_32x32x16_bf16 v[48:63], v[84:87], v[64:67], v[48:63]
	v_add_f32_e32 v68, v92, v68
	v_add_f32_e32 v68, v94, v68
	v_add_f32_e32 v68, v95, v68
	v_add_f32_e32 v68, v173, v68
	v_add_f32_e32 v68, v186, v68
	v_add_f32_e32 v68, v187, v68
	v_add_f32_e32 v68, v188, v68
	v_mfma_f32_32x32x16_bf16 v[32:47], v[88:91], v[64:67], v[32:47]
	v_add_f32_e32 v68, v189, v68
	v_add_f32_e32 v173, v190, v68
	v_mfma_f32_32x32x16_bf16 v[16:31], v[80:83], v[64:67], v[16:31]
	v_mfma_f32_32x32x16_bf16 v[0:15], v[76:79], v[64:67], v[0:15]
	v_and_b32_e32 v66, 7, v138
	v_lshl_add_u64 v[64:65], s[8:9], 0, v[150:151]
	v_lshlrev_b32_e32 v66, 4, v66
	v_mov_b32_e32 v67, v131
	v_lshl_add_u64 v[138:139], v[64:65], 0, v[66:67]
	v_lshl_add_u64 v[64:65], s[8:9], 0, v[148:149]
	s_lshl_b32 s8, s91, 4
	s_and_b32 s8, s8, 0x700
	s_add_u32 s8, s40, s8
	s_addc_u32 s9, s41, 0
	s_add_u32 s8, s8, 0x13840000
	s_addc_u32 s9, s9, 0
	v_lshl_add_u64 v[148:149], v[64:65], 0, v[66:67]
	v_lshl_add_u64 v[64:65], s[8:9], 0, v[144:145]
	v_lshl_add_u64 v[144:145], v[146:147], 1, v[64:65]
	v_lshl_add_u64 v[64:65], s[8:9], 0, v[140:141]
	v_lshl_add_u64 v[140:141], v[142:143], 1, v[64:65]
	v_mov_b32_e32 v142, v130
	s_add_i32 s98, s42, 0x13d08
	v_mov_b32_e32 v198, s98
	ds_read_b64 v[198:199], v198
	s_waitcnt lgkmcnt(0)
	v_sub_u32_e32 v198, v198, v172
	v_sub_u32_e32 v199, v199, v171
	s_nop 0
	v_readfirstlane_b32 s98, v198
	v_readfirstlane_b32 s99, v199
	s_branch .LBB0_616
; __device__ __forceinline__ unsigned cvt_pk_bf16(float lo, float hi) { f32x2_t f = {lo, hi}; bf16x2_t r = __builtin_convertvector(f, bf16x2_t); return __builtin_bit_cast(unsigned, r); }
; #define LAS __attribute__((address_space(3)))
; #define MFMA32(a, b, c) __builtin_amdgcn_mfma_f32_32x32x16_bf16((a), (b), (c), 0, 0, 0)
; template <bool DIFF> ...
;     ...
;             const int tmn = ((const LAS int*)(lds + TMM_OFF))[2 * kt], tmx = ((const LAS int*)(lds + TMM_OFF))[2 * kt + 1];
;             const bool far_hi = __builtin_amdgcn_readfirstlane(tmn - qmax4) >= 512, far_lo = __builtin_amdgcn_readfirstlane(tmx - qmin4) <= -512;
;     ...
;             for (int kb = 0; kb < 2; ++kb)
; #pragma unroll
;                 for (int i = 0; i < 16; ++i) { const float p = __builtin_amdgcn_exp2f(s[kb][i]); s[kb][i] = p; lsum += p; }
;         } else {
;             const bool need = mx > m_used + 8.0f;
;             if (__builtin_amdgcn_ballot_w64(need) != 0ull) {
;                 const float m_new = need ? mx : m_used;
;                 const float alpha = __builtin_amdgcn_exp2f(m_used - m_new);
;                 lsum *= alpha;
; #pragma unroll
;                 for (int d = 0; d < 4; ++d) O[d] = O[d] * alpha;
;                 m_used = m_new;
;             }
; #pragma unroll
;             for (int kb = 0; kb < 2; ++kb)
; #pragma unroll
;                 for (int i = 0; i < 16; ++i) { const float p = __builtin_amdgcn_exp2f(s[kb][i] - m_used); s[kb][i] = p; lsum += p; }
;         }
; #pragma unroll
;         for (int kb = 0; kb < 2; ++kb)
; #pragma unroll
;             for (int st = 0; st < 2; ++st) {
;                 u32x4 pw;
; #pragma unroll
;                 for (int q = 0; q < 4; ++q) pw[q] = cvt_pk_bf16(s[kb][8 * st + 2 * q], s[kb][8 * st + 2 * q + 1]);
;                 const bf16x8 pf = __builtin_bit_cast(bf16x8, pw);
;                 const LAS unsigned char* vp = vbuf + (r * VSTR + (2 * kb + st) * 16 + 8 * hh) * 2;
; #pragma unroll
;                 for (int d = 0; d < 4; ++d) { const bf16x8 vf = *(const LAS bf16x8*)(vp + d * 32 * VSTR * 2); O[d] = MFMA32(vf, pf, O[d]); }
;             }
;         if (more) store_tile((kt + 1) & 1);
;         __syncthreads();
.LBB0_615:
	v_add_u32_e32 v192, s9, v175
	v_exp_f32_e32 v143, v80
	v_exp_f32_e32 v146, v81
	v_exp_f32_e32 v147, v82
	v_exp_f32_e32 v150, v83
	ds_read_b128 v[80:83], v192 offset:17408
	ds_read_b128 v[176:179], v192 offset:17440
	v_exp_f32_e32 v151, v84
	v_exp_f32_e32 v193, v85
	v_exp_f32_e32 v194, v86
	v_exp_f32_e32 v195, v87
	v_cvt_pk_bf16_f32 v84, v143, v146
	v_cvt_pk_bf16_f32 v85, v147, v150
	v_cvt_pk_bf16_f32 v86, v151, v193
	v_cvt_pk_bf16_f32 v87, v194, v195
	v_add_f32_e32 v143, v173, v143
	v_add_f32_e32 v143, v146, v143
	s_waitcnt lgkmcnt(1)
	v_mfma_f32_32x32x16_bf16 v[48:63], v[80:83], v[84:87], v[48:63]
	ds_read_b128 v[80:83], v192 offset:22016
	ds_read_b128 v[180:183], v192 offset:22048
	v_add_f32_e32 v143, v147, v143
	v_add_f32_e32 v143, v150, v143
	v_exp_f32_e32 v88, v88
	v_exp_f32_e32 v89, v89
	v_add_f32_e32 v143, v151, v143
	v_add_f32_e32 v143, v193, v143
	s_waitcnt lgkmcnt(1)
	v_mfma_f32_32x32x16_bf16 v[32:47], v[80:83], v[84:87], v[32:47]
	ds_read_b128 v[80:83], v192 offset:26624
	ds_read_b128 v[184:187], v192 offset:31232
	ds_read_b128 v[188:191], v192 offset:26656
	v_exp_f32_e32 v90, v90
	v_add_f32_e32 v143, v194, v143
	v_exp_f32_e32 v91, v91
	v_add_f32_e32 v143, v195, v143
	v_exp_f32_e32 v92, v92
	v_exp_f32_e32 v93, v93
	s_waitcnt lgkmcnt(2)
	v_mfma_f32_32x32x16_bf16 v[16:31], v[80:83], v[84:87], v[16:31]
	v_exp_f32_e32 v94, v94
	v_exp_f32_e32 v95, v95
	ds_read_b128 v[80:83], v192 offset:31264
	v_exp_f32_e32 v146, v67
	v_exp_f32_e32 v147, v68
	v_exp_f32_e32 v150, v69
	v_exp_f32_e32 v151, v70
	s_waitcnt lgkmcnt(2)
	v_mfma_f32_32x32x16_bf16 v[0:15], v[184:187], v[84:87], v[0:15]
	v_cvt_pk_bf16_f32 v84, v88, v89
	v_add_f32_e32 v88, v88, v143
	v_add_f32_e32 v88, v89, v88
	v_add_f32_e32 v88, v90, v88
	v_add_f32_e32 v88, v91, v88
	v_add_f32_e32 v88, v92, v88
	v_cvt_pk_bf16_f32 v85, v90, v91
	v_cvt_pk_bf16_f32 v86, v92, v93
	v_cvt_pk_bf16_f32 v87, v94, v95
	v_add_f32_e32 v88, v93, v88
	v_exp_f32_e32 v92, v64
	v_exp_f32_e32 v93, v65
	v_exp_f32_e32 v143, v66
	ds_read_b128 v[64:67], v192 offset:17472
	v_mfma_f32_32x32x16_bf16 v[48:63], v[176:179], v[84:87], v[48:63]
	v_exp_f32_e32 v173, v71
	v_cvt_pk_bf16_f32 v68, v92, v93
	v_cvt_pk_bf16_f32 v69, v143, v146
	v_cvt_pk_bf16_f32 v70, v147, v150
	v_cvt_pk_bf16_f32 v71, v151, v173
	v_exp_f32_e32 v176, v73
	v_exp_f32_e32 v177, v74
	v_mfma_f32_32x32x16_bf16 v[32:47], v[180:183], v[84:87], v[32:47]
	v_exp_f32_e32 v178, v75
	v_exp_f32_e32 v179, v76
	v_exp_f32_e32 v180, v77
	v_exp_f32_e32 v181, v78
	v_exp_f32_e32 v182, v79
	s_cmp_eq_u32 s8, 1
	s_cselect_b32 s8, 0x8c00, 0
	s_waitcnt lgkmcnt(2)
	v_mfma_f32_32x32x16_bf16 v[16:31], v[188:191], v[84:87], v[16:31]
	s_add_i32 s8, s8, 0
	s_add_i32 s42, s42, 8
	s_add_i32 s43, s43, 1
	s_add_i32 s98, s42, 0x13d08
	v_mov_b32_e32 v198, s98
	ds_read_b64 v[198:199], v198
	v_add_u32_e32 v142, 0x100, v142
	v_lshl_add_u64 v[138:139], v[138:139], 0, s[34:35]
	v_lshl_add_u64 v[148:149], v[148:149], 0, s[34:35]
	v_lshl_add_u64 v[144:145], v[144:145], 0, s[36:37]
	s_waitcnt lgkmcnt(1)
	v_mfma_f32_32x32x16_bf16 v[0:15], v[80:83], v[84:87], v[0:15]
	ds_read_b128 v[80:83], v192 offset:22080
	ds_read_b128 v[84:87], v192 offset:17504
	s_cmp_eq_u32 s43, 32
	v_lshl_add_u64 v[140:141], v[140:141], 0, s[36:37]
	s_waitcnt lgkmcnt(2)
	v_mfma_f32_32x32x16_bf16 v[48:63], v[64:67], v[68:71], v[48:63]
	v_add_f32_e32 v64, v94, v88
	v_add_f32_e32 v94, v95, v64
	v_exp_f32_e32 v95, v72
	ds_read_b128 v[64:67], v192 offset:26688
	ds_read_b128 v[88:91], v192 offset:22112
	ds_read_b128 v[72:75], v192 offset:31296
	ds_read_b128 v[76:79], v192 offset:26720
	v_add_f32_e32 v92, v92, v94
	v_add_f32_e32 v92, v93, v92
	s_waitcnt lgkmcnt(5)
	v_mfma_f32_32x32x16_bf16 v[32:47], v[80:83], v[68:71], v[32:47]
	ds_read_b128 v[80:83], v192 offset:31328
	s_waitcnt lgkmcnt(4)
	v_mfma_f32_32x32x16_bf16 v[16:31], v[64:67], v[68:71], v[16:31]
	v_cvt_pk_bf16_f32 v64, v95, v176
	v_cvt_pk_bf16_f32 v65, v177, v178
	v_cvt_pk_bf16_f32 v66, v179, v180
	v_cvt_pk_bf16_f32 v67, v181, v182
	s_waitcnt lgkmcnt(2)
	v_mfma_f32_32x32x16_bf16 v[0:15], v[72:75], v[68:71], v[0:15]
	v_add_f32_e32 v68, v143, v92
	v_add_f32_e32 v68, v146, v68
	v_add_f32_e32 v68, v147, v68
	v_add_f32_e32 v68, v150, v68
	v_add_f32_e32 v68, v151, v68
	v_add_f32_e32 v68, v173, v68
	v_add_f32_e32 v68, v95, v68
	v_mfma_f32_32x32x16_bf16 v[48:63], v[84:87], v[64:67], v[48:63]
	v_add_f32_e32 v68, v176, v68
	v_add_f32_e32 v68, v177, v68
	v_add_f32_e32 v68, v178, v68
	v_add_f32_e32 v68, v179, v68
	v_add_f32_e32 v68, v180, v68
	v_add_f32_e32 v68, v181, v68
	v_add_f32_e32 v173, v182, v68
	v_mfma_f32_32x32x16_bf16 v[32:47], v[88:91], v[64:67], v[32:47]
	v_add3_u32 v68, s8, v167, v166
	v_add3_u32 v69, s8, v169, v168
	v_add_u32_e32 v70, s8, v164
	v_add_u32_e32 v71, s8, v165
	s_waitcnt vmcnt(3)
	ds_write_b128 v68, v[112:115]
	s_waitcnt vmcnt(2)
	ds_write_b128 v69, v[116:119]
	s_waitcnt vmcnt(1)
	ds_write_b128 v70, v[120:123] offset:17408
	s_waitcnt vmcnt(0)
	ds_write_b128 v71, v[124:127] offset:17408
	s_waitcnt lgkmcnt(0)
	v_sub_u32_e32 v198, v198, v172
	v_sub_u32_e32 v199, v199, v171
	s_nop 0
	v_readfirstlane_b32 s98, v198
	v_readfirstlane_b32 s99, v199
	s_barrier
	v_mfma_f32_32x32x16_bf16 v[16:31], v[76:79], v[64:67], v[16:31]
	v_mfma_f32_32x32x16_bf16 v[0:15], v[80:83], v[64:67], v[0:15]
	s_cbranch_scc1 .LBB0_622
; #define LAS __attribute__((address_space(3)))
; template <bool DIFF> ...
;     ...
;     auto load_tile = [&](int kt) {
; #pragma unroll
;         for (int i = 0; i < NKC; ++i) { const int c = tid + i * NTHREADS, row = c / CPR, cc = c % CPR; kreg[i] = *(const u32x4*)(Kb + (size_t)(kt * 64 + row) * KLD + cc * 8); }
; #pragma unroll
;         for (int i = 0; i < 2; ++i) { const int c = tid + i * NTHREADS, dv = c >> 3, cc = c & 7; vreg[i] = *(const u32x4*)(Vb + (size_t)dv * SEQ + kt * 64 + cc * 8); }
;     };
;     ...
;         if (more) load_tile(kt + 1);
;         LAS unsigned char* kbuf = lds + (kt & 1) * BUF; LAS unsigned char* vbuf = kbuf + K_BYTES;
;         f32x16 s[2];
;         if (DIFF) {
;             const int tmn = ((const LAS int*)(lds + TMM_OFF))[2 * kt], tmx = ((const LAS int*)(lds + TMM_OFF))[2 * kt + 1];
;             const bool far_hi = __builtin_amdgcn_readfirstlane(tmn - qmax4) >= 512, far_lo = __builtin_amdgcn_readfirstlane(tmx - qmin4) <= -512;
;             if (far_hi || far_lo) {
;                 const float cb = (far_hi ? bias_hi : bias_lo) + nm;
; #pragma unroll
;                 for (int kb = 0; kb < 2; ++kb)
; #pragma unroll
;                     for (int i = 0; i < 16; ++i) s[kb][i] = cb;
;             } else {
; #pragma unroll
;                 for (int kb = 0; kb < 2; ++kb) {
;                     const LAS int* P4 = (const LAS int*)(lds + POS_OFF) + kt * 64 + 32 * kb + 4 * hh;
; #pragma unroll
;                     for (int g = 0; g < 4; ++g) { const i32x4 pk = *(const LAS i32x4*)(P4 + 8 * g);
; #pragma unroll
;                         for (int j = 0; j < 4; ++j) { int d = pk[j] - pq4; d = d < -512 ? -512 : (d > 512 ? 512 : d); s[kb][4 * g + j] = *(const LAS float*)(lds + LUT_OFF + 512 + d) + nm; } }
;                 }
.LBB0_616:
	v_lshl_add_u64 v[64:65], s[12:13], 0, v[140:141]
	v_lshl_add_u64 v[66:67], s[12:13], 0, v[144:145]
	global_load_dwordx4 v[112:115], v[64:65], off
	global_load_dwordx4 v[116:119], v[66:67], off
	v_lshl_add_u64 v[64:65], s[12:13], 0, v[148:149]
	v_lshl_add_u64 v[66:67], s[12:13], 0, v[138:139]
	global_load_dwordx4 v[120:123], v[64:65], off
	global_load_dwordx4 v[124:127], v[66:67], off
	s_cmpk_gt_i32 s98, 0x1ff
	s_cselect_b64 s[8:9], -1, 0
	s_cmpk_lt_i32 s99, 0xfe01
	s_cselect_b64 s[40:41], -1, 0
	s_or_b64 s[48:49], s[8:9], s[40:41]
	s_mov_b64 s[40:41], -1
	s_and_b64 vcc, exec, s[48:49]
	s_cbranch_vccnz .LBB0_618
	v_add_u32_e32 v72, 0, v142
	v_add_u32_e32 v64, 0x11900, v72
	ds_read_b128 v[64:67], v64
	v_add_u32_e32 v68, 0x11920, v72
	ds_read_b128 v[68:71], v68
	s_mov_b64 s[40:41], 0
	s_waitcnt lgkmcnt(1)
	v_sub_u32_e32 v64, v64, v162
	v_med3_i32 v64, v64, s75, v158
	v_add_u32_e32 v73, s84, v64
	v_sub_u32_e32 v64, v66, v162
	v_med3_i32 v64, v64, s75, v158
	v_add_u32_e32 v75, s84, v64
	v_sub_u32_e32 v64, v67, v162
	v_med3_i32 v64, v64, s75, v158
	v_add_u32_e32 v76, s84, v64
	s_waitcnt lgkmcnt(0)
	v_sub_u32_e32 v64, v68, v162
	v_med3_i32 v64, v64, s75, v158
	v_add_u32_e32 v68, s84, v64
	v_sub_u32_e32 v64, v69, v162
	v_med3_i32 v64, v64, s75, v158
	v_add_u32_e32 v69, s84, v64
	v_sub_u32_e32 v64, v70, v162
	v_med3_i32 v64, v64, s75, v158
	v_add_u32_e32 v70, s84, v64
	v_sub_u32_e32 v64, v71, v162
	v_sub_u32_e32 v65, v65, v162
	v_med3_i32 v64, v64, s75, v158
	v_med3_i32 v65, v65, s75, v158
	v_add_u32_e32 v71, s84, v64
	v_add_u32_e32 v64, 0x11940, v72
	v_add_u32_e32 v74, s84, v65
	ds_read_b128 v[64:67], v64
	ds_read_b32 v80, v73
	ds_read_b32 v81, v74
	ds_read_b32 v82, v75
	ds_read_b32 v83, v76
	ds_read_b32 v84, v68
	ds_read_b32 v85, v69
	ds_read_b32 v86, v70
	ds_read_b32 v87, v71
	s_waitcnt lgkmcnt(8)
	v_sub_u32_e32 v64, v64, v162
	v_med3_i32 v64, v64, s75, v158
	v_add_u32_e32 v68, 0x11960, v72
	v_add_u32_e32 v73, s84, v64
	v_sub_u32_e32 v64, v65, v162
	ds_read_b128 v[68:71], v68
	v_med3_i32 v64, v64, s75, v158
	v_add_u32_e32 v74, s84, v64
	v_sub_u32_e32 v64, v66, v162
	v_med3_i32 v64, v64, s75, v158
	v_add_u32_e32 v75, s84, v64
	v_sub_u32_e32 v64, v67, v162
	v_med3_i32 v64, v64, s75, v158
	v_add_u32_e32 v76, s84, v64
	s_waitcnt lgkmcnt(0)
	v_sub_u32_e32 v64, v68, v162
	v_med3_i32 v64, v64, s75, v158
	v_add_u32_e32 v68, s84, v64
	v_sub_u32_e32 v64, v69, v162
	v_med3_i32 v64, v64, s75, v158
	v_add_u32_e32 v69, s84, v64
	v_sub_u32_e32 v64, v70, v162
	v_med3_i32 v64, v64, s75, v158
	v_add_u32_e32 v70, s84, v64
	v_sub_u32_e32 v64, v71, v162
	v_med3_i32 v64, v64, s75, v158
	v_add_u32_e32 v71, s84, v64
	v_add_u32_e32 v64, 0x11980, v72
	ds_read_b128 v[64:67], v64
	ds_read_b32 v88, v73
	ds_read_b32 v89, v74
	ds_read_b32 v90, v75
	ds_read_b32 v91, v76
	ds_read_b32 v92, v68
	ds_read_b32 v93, v69
	ds_read_b32 v94, v70
	ds_read_b32 v95, v71
	s_waitcnt lgkmcnt(8)
	v_sub_u32_e32 v64, v64, v162
	v_med3_i32 v64, v64, s75, v158
	v_add_u32_e32 v68, 0x119a0, v72
	v_add_u32_e32 v73, s84, v64
	v_sub_u32_e32 v64, v65, v162
	ds_read_b128 v[68:71], v68
	v_med3_i32 v64, v64, s75, v158
	v_add_u32_e32 v74, s84, v64
	v_sub_u32_e32 v64, v66, v162
	v_med3_i32 v64, v64, s75, v158
	v_add_u32_e32 v75, s84, v64
	v_sub_u32_e32 v64, v67, v162
	v_med3_i32 v64, v64, s75, v158
	v_add_u32_e32 v76, s84, v64
	s_waitcnt lgkmcnt(0)
	v_sub_u32_e32 v64, v68, v162
	v_med3_i32 v64, v64, s75, v158
	v_add_u32_e32 v77, s84, v64
	v_sub_u32_e32 v64, v69, v162
	v_med3_i32 v64, v64, s75, v158
	v_add_u32_e32 v78, s84, v64
	v_sub_u32_e32 v64, v70, v162
	v_sub_u32_e32 v68, v71, v162
	v_med3_i32 v64, v64, s75, v158
	v_med3_i32 v68, v68, s75, v158
	v_add_u32_e32 v79, s84, v64
	v_add_u32_e32 v64, 0x119c0, v72
	v_add_u32_e32 v143, s84, v68
	v_add_u32_e32 v68, 0x119e0, v72
	ds_read_b128 v[64:67], v64
	ds_read_b128 v[68:71], v68
	v_pk_add_f32 v[94:95], v[136:137], v[94:95] op_sel_hi:[0,1]
	v_pk_add_f32 v[92:93], v[136:137], v[92:93] op_sel_hi:[0,1]
	v_pk_add_f32 v[90:91], v[136:137], v[90:91] op_sel_hi:[0,1]
	s_waitcnt lgkmcnt(1)
	v_sub_u32_e32 v64, v64, v162
	v_sub_u32_e32 v65, v65, v162
	v_sub_u32_e32 v66, v66, v162
	v_sub_u32_e32 v67, v67, v162
	s_waitcnt lgkmcnt(0)
	v_sub_u32_e32 v68, v68, v162
	v_sub_u32_e32 v69, v69, v162
	v_sub_u32_e32 v70, v70, v162
	v_sub_u32_e32 v71, v71, v162
	v_med3_i32 v64, v64, s75, v158
	v_med3_i32 v65, v65, s75, v158
	v_med3_i32 v66, v66, s75, v158
	v_med3_i32 v67, v67, s75, v158
	v_med3_i32 v68, v68, s75, v158
	v_med3_i32 v69, v69, s75, v158
	v_med3_i32 v70, v70, s75, v158
	v_med3_i32 v71, v71, s75, v158
	v_add_u32_e32 v64, s84, v64
	v_add_u32_e32 v65, s84, v65
	v_add_u32_e32 v66, s84, v66
	v_add_u32_e32 v67, s84, v67
	v_add_u32_e32 v68, s84, v68
	v_add_u32_e32 v69, s84, v69
	v_add_u32_e32 v70, s84, v70
	v_add_u32_e32 v71, s84, v71
	ds_read_b32 v64, v64
	ds_read_b32 v65, v65
	ds_read_b32 v66, v66
	ds_read_b32 v67, v67
	ds_read_b32 v68, v68
	ds_read_b32 v69, v69
	ds_read_b32 v70, v70
	ds_read_b32 v71, v71
	ds_read_b32 v146, v73
	ds_read_b32 v147, v74
	ds_read_b32 v150, v75
	ds_read_b32 v151, v76
	ds_read_b32 v176, v77
	ds_read_b32 v177, v78
	ds_read_b32 v178, v79
	ds_read_b32 v179, v143
	s_waitcnt lgkmcnt(8)
	v_pk_add_f32 v[78:79], v[136:137], v[70:71] op_sel_hi:[0,1]
	v_pk_add_f32 v[76:77], v[136:137], v[68:69] op_sel_hi:[0,1]
	v_pk_add_f32 v[74:75], v[136:137], v[66:67] op_sel_hi:[0,1]
	v_pk_add_f32 v[72:73], v[136:137], v[64:65] op_sel_hi:[0,1]
	s_waitcnt lgkmcnt(0)
	v_pk_add_f32 v[70:71], v[136:137], v[178:179] op_sel_hi:[0,1]
	v_pk_add_f32 v[68:69], v[136:137], v[176:177] op_sel_hi:[0,1]
	v_pk_add_f32 v[66:67], v[136:137], v[150:151] op_sel_hi:[0,1]
	v_pk_add_f32 v[64:65], v[136:137], v[146:147] op_sel_hi:[0,1]
	v_pk_add_f32 v[88:89], v[136:137], v[88:89] op_sel_hi:[0,1]
	v_pk_add_f32 v[86:87], v[136:137], v[86:87] op_sel_hi:[0,1]
	v_pk_add_f32 v[84:85], v[136:137], v[84:85] op_sel_hi:[0,1]
	v_pk_add_f32 v[82:83], v[136:137], v[82:83] op_sel_hi:[0,1]
	v_pk_add_f32 v[80:81], v[136:137], v[80:81] op_sel_hi:[0,1]
